# layer-1 w_in GEMM main tiles: XCDs 8 decode positions apart (was 6); layer 0 stays at 6
# baseline (speedup 1.0000x reference)
.Lgi_sk_rm:
	s_and_b32 s0, s57, 7
	s_lshr_b32 s1, s57, 3
	s_cmpk_ge_u32 s1, 192
	s_cbranch_scc1 .Lgi_sk_nr
	s_mul_i32 s57, s0, 2
	s_add_u32 s1, s1, s57
	s_mul_i32 s57, s1, 0x5556
	s_lshr_b32 s57, s57, 22
	s_mul_i32 s57, s57, 192
	s_sub_u32 s1, s1, s57
